# attention: next-tile row-max and the row-sum adds moved into the PV MFMA shadow (V fragments double-buffered in two batches)
# speedup vs baseline: 1.0093x; 1.0093x over previous
; #define MX3(a, b, c) __builtin_fmaxf(__builtin_fmaxf((a), (b)), (c))
; __device__ __forceinline__ void attn_unit(const Params& P, unsigned char* lds, int h, int qb) {
;     ...
;             float mx = MX3(c0[0], c0[1], c1[0]);
;             mx = MX3(mx, c1[1], c0[2]);
; #pragma unroll
;             for (int r = 2; r < 16; r += 2) { mx = MX3(mx, c0[r], c0[r + 1]); mx = MX3(mx, c1[r], c1[r + 1]); }
;             mx = fmaxf(mx, __shfl_xor(mx, 32));
;     ...
;         if (act) {
;             lsum += ps0 + ps1;
;             const unsigned char* Vb = lds + 2 * KBUF + (t & 1) * VBUF;
; #pragma unroll
;             for (int ks = 0; ks < 4; ++ks) {
;                 const bf16x8 pa = __builtin_bit_cast(bf16x8, pw[ks]);
;                 const unsigned char* va = Vb + r32 * VROW + (16 * ks + 4 * hi) * 2;
;                 const v2u l0 = *(const v2u*)va, h0 = *(const v2u*)(va + 16);
;                 const v2u l1 = *(const v2u*)(va + 32 * VROW), h1 = *(const v2u*)(va + 32 * VROW + 16);
;                 const bf16x8 vf0 = __builtin_bit_cast(bf16x8, ((v4u){l0.x, l0.y, h0.x, h0.y}));
;                 const bf16x8 vf1 = __builtin_bit_cast(bf16x8, ((v4u){l1.x, l1.y, h1.x, h1.y}));
;                 o0 = __builtin_amdgcn_mfma_f32_32x32x16_bf16(vf0, pa, o0, 0, 0, 0);
;                 o1 = __builtin_amdgcn_mfma_f32_32x32x16_bf16(vf1, pa, o1, 0, 0, 0);
;             }
;         }
.LBB0_884:
	s_bitcmp1_b32 s21, 0
	s_cselect_b32 s8, 0x2200, 0
	v_add_u32_e32 v142, s8, v250
	v_add_u32_e32 v143, 0x7800, v142
	v_add_u32_e32 v142, 0x6800, v142
	ds_read2_b64 v[112:115], v142 offset1:2
	ds_read2_b64 v[116:119], v143 offset0:32 offset1:34
	ds_read2_b64 v[120:123], v142 offset0:4 offset1:6
	ds_read2_b64 v[124:127], v143 offset0:36 offset1:38
	v_pk_add_f32 v[14:15], v[14:15], 0 op_sel_hi:[1,0]
	s_nop 0
	v_pk_add_f32 v[14:15], v[14:15], v[128:129]
	s_nop 0
	v_pk_add_f32 v[14:15], v[14:15], v[130:131]
	s_nop 0
	v_pk_add_f32 v[14:15], v[14:15], v[132:133]
	s_nop 0
	v_pk_add_f32 v[14:15], v[14:15], v[134:135]
	s_nop 0
	v_pk_add_f32 v[14:15], v[14:15], v[136:137]
	s_nop 0
	v_pk_add_f32 v[14:15], v[14:15], v[138:139]
	s_nop 0
	v_pk_add_f32 v[14:15], v[14:15], v[140:141]
	ds_read2_b64 v[128:131], v142 offset0:8 offset1:10
	ds_read2_b64 v[132:135], v143 offset0:40 offset1:42
	ds_read2_b64 v[136:139], v142 offset0:12 offset1:14
	s_waitcnt lgkmcnt(6)
	v_mfma_f32_32x32x16_bf16 v[48:63], v[112:115], v[2:5], v[48:63]
	v_max3_f32 v140, v16, v17, v80
	v_max3_f32 v141, v81, v18, v19
	v_pk_add_f32 v[14:15], v[14:15], v[96:97]
	s_waitcnt lgkmcnt(5)
	v_mfma_f32_32x32x16_bf16 v[32:47], v[116:119], v[2:5], v[32:47]
	ds_read2_b64 v[112:115], v143 offset0:44 offset1:46
	v_max3_f32 v140, v140, v82, v83
	v_pk_add_f32 v[14:15], v[14:15], v[98:99]
	v_max3_f32 v141, v141, v20, v21
	s_waitcnt lgkmcnt(5)
	v_mfma_f32_32x32x16_bf16 v[48:63], v[120:123], v[6:9], v[48:63]
	v_pk_add_f32 v[14:15], v[14:15], v[100:101]
	v_max3_f32 v140, v140, v84, v85
	v_pk_add_f32 v[14:15], v[14:15], v[102:103]
	s_waitcnt lgkmcnt(4)
	v_mfma_f32_32x32x16_bf16 v[32:47], v[124:127], v[6:9], v[32:47]
	v_max3_f32 v141, v141, v22, v23
	v_pk_add_f32 v[14:15], v[14:15], v[104:105]
	v_max3_f32 v140, v140, v86, v87
	s_waitcnt lgkmcnt(3)
	v_mfma_f32_32x32x16_bf16 v[48:63], v[128:131], v[10:13], v[48:63]
	v_pk_add_f32 v[14:15], v[14:15], v[106:107]
	v_max3_f32 v141, v141, v24, v25
	v_pk_add_f32 v[14:15], v[14:15], v[108:109]
	s_waitcnt lgkmcnt(2)
	v_mfma_f32_32x32x16_bf16 v[32:47], v[132:135], v[10:13], v[32:47]
	v_max3_f32 v140, v140, v88, v89
	v_pk_add_f32 v[14:15], v[14:15], v[110:111]
	v_max3_f32 v141, v141, v26, v27
	s_waitcnt lgkmcnt(1)
	v_mfma_f32_32x32x16_bf16 v[48:63], v[136:139], v[180:183], v[48:63]
	v_max3_f32 v140, v140, v90, v91
	v_max3_f32 v141, v141, v28, v29
	v_max3_f32 v140, v140, v92, v93
	s_waitcnt lgkmcnt(0)
	v_mfma_f32_32x32x16_bf16 v[32:47], v[112:115], v[180:183], v[32:47]
	v_max3_f32 v141, v141, v30, v31
	v_max3_f32 v140, v140, v94, v95
	v_max_f32_e32 v98, v140, v141
	v_add_f32_e32 v96, v14, v15
	v_add_f32_e32 v236, v236, v96
	s_branch .LBB0_896
.LBB0_885:
	v_max3_f32 v98, v16, v17, v80
	v_max3_f32 v99, v81, v18, v19
	v_max3_f32 v98, v98, v82, v83
	v_max3_f32 v99, v99, v20, v21
	v_max3_f32 v98, v98, v84, v85
	v_max3_f32 v99, v99, v22, v23
	v_max3_f32 v98, v98, v86, v87
	v_max3_f32 v99, v99, v24, v25
	v_max3_f32 v98, v98, v88, v89
	v_max3_f32 v99, v99, v26, v27
	v_max3_f32 v98, v98, v90, v91
	v_max3_f32 v99, v99, v28, v29
	v_max3_f32 v98, v98, v92, v93
	v_max3_f32 v99, v99, v30, v31
	v_max3_f32 v98, v98, v94, v95
	v_max_f32_e32 v98, v98, v99
.Lattn_mx:
	v_mov_b32_e32 v3, v98
	v_mov_b32_e32 v4, v98
	s_cmp_eq_u32 s21, 0
	s_nop 0
	v_permlane32_swap_b32_e32 v3, v4
	v_max3_f32 v2, v98, v3, v4
	s_cbranch_scc1 .LBB0_888
	s_mov_b32 s10, 0x41000000
	v_cmp_lt_f32_e32 vcc, s10, v2
	s_cbranch_vccz .LBB0_890
	v_max_f32_e32 v2, v2, v2
	v_max_f32_e32 v2, 0, v2

; #define MX3(a, b, c) __builtin_fmaxf(__builtin_fmaxf((a), (b)), (c))
; __device__ __forceinline__ void attn_unit(const Params& P, unsigned char* lds, int h, int qb) {
;     ...
;             float mx = MX3(c0[0], c0[1], c1[0]);
;             mx = MX3(mx, c1[1], c0[2]);
; #pragma unroll
;             for (int r = 2; r < 16; r += 2) { mx = MX3(mx, c0[r], c0[r + 1]); mx = MX3(mx, c1[r], c1[r + 1]); }
;             mx = fmaxf(mx, __shfl_xor(mx, 32));
;     ...
;         if (act) {
;             lsum += ps0 + ps1;
;             const unsigned char* Vb = lds + 2 * KBUF + (t & 1) * VBUF;
; #pragma unroll
;             for (int ks = 0; ks < 4; ++ks) {
;                 const bf16x8 pa = __builtin_bit_cast(bf16x8, pw[ks]);
;                 const unsigned char* va = Vb + r32 * VROW + (16 * ks + 4 * hi) * 2;
;                 const v2u l0 = *(const v2u*)va, h0 = *(const v2u*)(va + 16);
;                 const v2u l1 = *(const v2u*)(va + 32 * VROW), h1 = *(const v2u*)(va + 32 * VROW + 16);
;                 const bf16x8 vf0 = __builtin_bit_cast(bf16x8, ((v4u){l0.x, l0.y, h0.x, h0.y}));
;                 const bf16x8 vf1 = __builtin_bit_cast(bf16x8, ((v4u){l1.x, l1.y, h1.x, h1.y}));
;                 o0 = __builtin_amdgcn_mfma_f32_32x32x16_bf16(vf0, pa, o0, 0, 0, 0);
;                 o1 = __builtin_amdgcn_mfma_f32_32x32x16_bf16(vf1, pa, o1, 0, 0, 0);
;             }
;         }
.LBB0_894:
	s_andn2_b64 vcc, exec, s[8:9]
	s_cbranch_vccnz .LBB0_896
	s_bitcmp1_b32 s21, 0
	s_cselect_b32 s8, 0x2200, 0
	v_add_u32_e32 v14, s8, v250
	v_add_u32_e32 v15, 0x6800, v14
	v_add_u32_e32 v14, 0x7800, v14
	ds_read2_b64 v[112:115], v15 offset1:2
	ds_read2_b64 v[116:119], v14 offset0:32 offset1:34
	ds_read2_b64 v[120:123], v15 offset0:4 offset1:6
	ds_read2_b64 v[124:127], v14 offset0:36 offset1:38
	ds_read2_b64 v[128:131], v15 offset0:8 offset1:10
	ds_read2_b64 v[132:135], v14 offset0:40 offset1:42
	ds_read2_b64 v[136:139], v15 offset0:12 offset1:14
	ds_read2_b64 v[140:143], v14 offset0:44 offset1:46
	v_add_f32_e32 v96, v230, v231
	v_add_f32_e32 v236, v236, v96
	s_waitcnt lgkmcnt(7)
	v_mfma_f32_32x32x16_bf16 v[48:63], v[112:115], v[2:5], v[48:63]
	v_max3_f32 v98, v16, v17, v80
	v_max3_f32 v99, v81, v18, v19
	s_waitcnt lgkmcnt(6)
	v_mfma_f32_32x32x16_bf16 v[32:47], v[116:119], v[2:5], v[32:47]
	v_max3_f32 v98, v98, v82, v83
	v_max3_f32 v99, v99, v20, v21
	s_waitcnt lgkmcnt(5)
	v_mfma_f32_32x32x16_bf16 v[48:63], v[120:123], v[6:9], v[48:63]
	v_max3_f32 v98, v98, v84, v85
	v_max3_f32 v99, v99, v22, v23
	s_waitcnt lgkmcnt(4)
	v_mfma_f32_32x32x16_bf16 v[32:47], v[124:127], v[6:9], v[32:47]
	v_max3_f32 v98, v98, v86, v87
	v_max3_f32 v99, v99, v24, v25
	s_waitcnt lgkmcnt(3)
	v_mfma_f32_32x32x16_bf16 v[48:63], v[128:131], v[10:13], v[48:63]
	v_max3_f32 v98, v98, v88, v89
	v_max3_f32 v99, v99, v26, v27
	s_waitcnt lgkmcnt(2)
	v_mfma_f32_32x32x16_bf16 v[32:47], v[132:135], v[10:13], v[32:47]
	v_max3_f32 v98, v98, v90, v91
	v_max3_f32 v99, v99, v28, v29
	s_waitcnt lgkmcnt(1)
	v_mfma_f32_32x32x16_bf16 v[48:63], v[136:139], v[180:183], v[48:63]
	v_max3_f32 v98, v98, v92, v93
	v_max3_f32 v99, v99, v30, v31
	s_waitcnt lgkmcnt(0)
	v_mfma_f32_32x32x16_bf16 v[32:47], v[140:143], v[180:183], v[32:47]
	v_max3_f32 v98, v98, v94, v95
	v_max_f32_e32 v98, v98, v99
